# in-proj K-loop: B0 LDS fragment reads moved one phase earlier into MFMA shadow (+vmcnt(10) cover)
# speedup vs baseline: 1.0063x; 1.0063x over previous
; #define PG8_STAGE(bufoff, gbase, voff) do { _Pragma("unroll") for (int _i = 0; _i < 2; ++_i) \
;         __builtin_amdgcn_global_load_lds((const unsigned*)((const char*)(gbase) + (voff)[_i]), (LAS unsigned*)(lds + (bufoff) + ldsw + _i * 8192), 16, 0, 0); } while (0)
; #define PG8_LDA(dst, b, h) do { _Pragma("unroll") for (int m = 0; m < 4; ++m) _Pragma("unroll") for (int k = 0; k < 2; ++k) dst[m][k] = *(const LAS bf16x8*)(lds + PG8_SA(b, h) + aoff + m * 2048 + k * 1024); } while (0)
; #define PG8_LDB(dst, b, h) do { _Pragma("unroll") for (int n = 0; n < 2; ++n) _Pragma("unroll") for (int k = 0; k < 2; ++k) dst[n][k] = *(const LAS bf16x8*)(lds + PG8_SB(b, h) + boff + n * 2048 + k * 1024); } while (0)
; #define PG8_WAIT_L(n) asm volatile("s_waitcnt lgkmcnt(" #n ")" ::: "memory")
; #define PG8_BAR __builtin_amdgcn_s_barrier()
; #define PG8_SCHED __builtin_amdgcn_sched_barrier(0)
; template <class Epi, class Sched>
; __device__ __forceinline__ void gemm_phase(const int wv, LAS unsigned char* lds, const Gemm g, const Sched& S, const Epi& E) {
;     ...
;         const bool has_next = S.next(ui + 1, nxt);
;         const char* nA = has_next ? (const char*)g.A + (size_t)nxt.pm * tstepA : cA; const char* nB = has_next ? (const char*)g.Bt + (size_t)nxt.pn * tstepB : cB;
;         for (int t = 0; t < nt; t += 2) {
;             const bool last = (t == nt - 2);
;             const char* a1 = cA + (size_t)(t + 1) * kstepA;
;             const char* a2 = last ? nA : cA + (size_t)(t + 2) * kstepA; const char* b2 = last ? nB : cB + (size_t)(t + 2) * kstep;
;             const char* a3 = a2 + kstepA; const char* b3 = b2 + kstep;
;             if (last && has_next) S.a_ready(nxt);
;             PG8_LDB(B0, 0, 0); PG8_SCHED; PG8_LDA(At, 0, 0); PG8_STAGE(PG8_SA(1, 1), a1 + hstepA, voffA);
;             PG8_WAIT_L(8); PG8_BAR; PG8_WAIT_L(0); PG8_MMA(0, 0, At, B0); PG8_BAR; PG8_SCHED;
;     ...
; #pragma unroll
;         for (int a = 0; a < 2; ++a)
; #pragma unroll
;             for (int b = 0; b < 2; ++b)
; #pragma unroll
;                 for (int m = 0; m < 4; ++m)
; #pragma unroll
;                     for (int n = 0; n < 2; ++n) acc[a][b][m][n] = (f32x4){0.f, 0.f, 0.f, 0.f};
;         cur = nxt; cA = nA; cB = nB; ++ui;
.LBB0_146:
	s_ashr_i32 s15, s14, 31
	s_xor_b64 s[18:19], s[26:27], -1
	s_lshl_b64 s[16:17], s[14:15], 19
	s_add_u32 s16, s42, s16
	s_addc_u32 s17, s43, s17
	s_and_b64 s[20:21], s[26:27], exec
	s_cselect_b32 s1, s17, s23
	s_cselect_b32 s3, s16, s22
	s_ashr_i32 s13, s12, 31
	s_lshl_b64 s[20:21], s[12:13], 19
	s_add_u32 s20, s6, s20
	s_addc_u32 s21, s7, s21
	s_and_b64 s[26:27], s[26:27], exec
	s_cselect_b32 s13, s21, s25
	s_cselect_b32 s15, s20, s24
	s_add_u32 s22, s22, 0x40080
	s_addc_u32 s23, s23, 0
	s_add_u32 s28, s24, 0x100
	v_mov_b32_e32 v2, 0
	s_addc_u32 s29, s25, 0
	s_mov_b32 s30, -2
	v_mov_b32_e32 v3, v2
	v_mov_b32_e32 v4, v2
	v_mov_b32_e32 v5, v2
	v_mov_b32_e32 v6, v2
	v_mov_b32_e32 v7, v2
	v_mov_b32_e32 v8, v2
	v_mov_b32_e32 v9, v2
	v_mov_b32_e32 v18, v2
	v_mov_b32_e32 v19, v2
	v_mov_b32_e32 v20, v2
	v_mov_b32_e32 v21, v2
	v_mov_b32_e32 v22, v2
	v_mov_b32_e32 v23, v2
	v_mov_b32_e32 v24, v2
	v_mov_b32_e32 v25, v2
	v_mov_b32_e32 v34, v2
	v_mov_b32_e32 v35, v2
	v_mov_b32_e32 v36, v2
	v_mov_b32_e32 v37, v2
	v_mov_b32_e32 v38, v2
	v_mov_b32_e32 v39, v2
	v_mov_b32_e32 v40, v2
	v_mov_b32_e32 v41, v2
	v_mov_b32_e32 v50, v2
	v_mov_b32_e32 v51, v2
	v_mov_b32_e32 v52, v2
	v_mov_b32_e32 v53, v2
	v_mov_b32_e32 v54, v2
	v_mov_b32_e32 v55, v2
	v_mov_b32_e32 v56, v2
	v_mov_b32_e32 v57, v2
	v_mov_b32_e32 v10, v2
	v_mov_b32_e32 v11, v2
	v_mov_b32_e32 v12, v2
	v_mov_b32_e32 v13, v2
	v_mov_b32_e32 v14, v2
	v_mov_b32_e32 v15, v2
	v_mov_b32_e32 v16, v2
	v_mov_b32_e32 v17, v2
	v_mov_b32_e32 v26, v2
	v_mov_b32_e32 v27, v2
	v_mov_b32_e32 v28, v2
	v_mov_b32_e32 v29, v2
	v_mov_b32_e32 v30, v2
	v_mov_b32_e32 v31, v2
	v_mov_b32_e32 v32, v2
	v_mov_b32_e32 v33, v2
	v_mov_b32_e32 v42, v2
	v_mov_b32_e32 v43, v2
	v_mov_b32_e32 v44, v2
	v_mov_b32_e32 v45, v2
	v_mov_b32_e32 v46, v2
	v_mov_b32_e32 v47, v2
	v_mov_b32_e32 v48, v2
	v_mov_b32_e32 v49, v2
	v_mov_b32_e32 v58, v2
	v_mov_b32_e32 v59, v2
	v_mov_b32_e32 v60, v2
	v_mov_b32_e32 v61, v2
	v_mov_b32_e32 v62, v2
	v_mov_b32_e32 v63, v2
	v_mov_b32_e32 v64, v2
	v_mov_b32_e32 v65, v2
	v_mov_b32_e32 v66, v2
	v_mov_b32_e32 v67, v2
	v_mov_b32_e32 v68, v2
	v_mov_b32_e32 v69, v2
	v_mov_b32_e32 v70, v2
	v_mov_b32_e32 v71, v2
	v_mov_b32_e32 v72, v2
	v_mov_b32_e32 v73, v2
	v_mov_b32_e32 v82, v2
	v_mov_b32_e32 v83, v2
	v_mov_b32_e32 v84, v2
	v_mov_b32_e32 v85, v2
	v_mov_b32_e32 v86, v2
	v_mov_b32_e32 v87, v2
	v_mov_b32_e32 v88, v2
	v_mov_b32_e32 v89, v2
	v_mov_b32_e32 v98, v2
	v_mov_b32_e32 v99, v2
	v_mov_b32_e32 v100, v2
	v_mov_b32_e32 v101, v2
	v_mov_b32_e32 v102, v2
	v_mov_b32_e32 v103, v2
	v_mov_b32_e32 v104, v2
	v_mov_b32_e32 v105, v2
	v_mov_b32_e32 v114, v2
	v_mov_b32_e32 v115, v2
	v_mov_b32_e32 v116, v2
	v_mov_b32_e32 v117, v2
	v_mov_b32_e32 v118, v2
	v_mov_b32_e32 v119, v2
	v_mov_b32_e32 v120, v2
	v_mov_b32_e32 v121, v2
	v_mov_b32_e32 v74, v2
	v_mov_b32_e32 v75, v2
	v_mov_b32_e32 v76, v2
	v_mov_b32_e32 v77, v2
	v_mov_b32_e32 v78, v2
	v_mov_b32_e32 v79, v2
	v_mov_b32_e32 v80, v2
	v_mov_b32_e32 v81, v2
	v_mov_b32_e32 v90, v2
	v_mov_b32_e32 v91, v2
	v_mov_b32_e32 v92, v2
	v_mov_b32_e32 v93, v2
	v_mov_b32_e32 v94, v2
	v_mov_b32_e32 v95, v2
	v_mov_b32_e32 v96, v2
	v_mov_b32_e32 v97, v2
	v_mov_b32_e32 v106, v2
	v_mov_b32_e32 v107, v2
	v_mov_b32_e32 v108, v2
	v_mov_b32_e32 v109, v2
	v_mov_b32_e32 v110, v2
	v_mov_b32_e32 v111, v2
	v_mov_b32_e32 v112, v2
	v_mov_b32_e32 v113, v2
	v_mov_b32_e32 v122, v2
	v_mov_b32_e32 v123, v2
	v_mov_b32_e32 v124, v2
	v_mov_b32_e32 v125, v2
	v_mov_b32_e32 v126, v2
	v_mov_b32_e32 v127, v2
	v_mov_b32_e32 v128, v2
	v_mov_b32_e32 v129, v2
	v_add_u32_e32 v150, 0x10000, v152
	ds_read_b128 v[142:145], v150
	ds_read_b128 v[146:149], v150 offset:1024
	ds_read_b128 v[160:163], v150 offset:2048
	ds_read_b128 v[164:167], v150 offset:3072
.LBB0_147:
	s_add_u32 s24, s22, 0xfffc0080
	s_addc_u32 s25, s23, -1
	s_add_i32 s31, 0, 0x10000
	s_cmp_eq_u32 s30, 12
	s_cselect_b32 s27, s1, s25
	s_cselect_b32 s26, s3, s24
	s_cselect_b32 s25, s13, s29
	s_cselect_b32 s24, s15, s28
	v_lshl_add_u64 v[150:151], s[22:23], 0, v[138:139]
	s_add_i32 m0, s45, 0xc000
	ds_read_b128 v[168:171], v158
	ds_read_b128 v[172:175], v158 offset:1024
	ds_read_b128 v[180:183], v158 offset:2048
	ds_read_b128 v[192:195], v158 offset:3072
	ds_read_b128 v[196:199], v158 offset:4096
	ds_read_b128 v[200:203], v158 offset:5120
	ds_read_b128 v[204:207], v158 offset:6144
	ds_read_b128 v[208:211], v158 offset:7168
	global_load_lds_dwordx4 v[150:151], off
	v_lshl_add_u64 v[150:151], s[22:23], 0, v[140:141]
	s_add_i32 m0, s45, 0xe000
	s_nop 0
	global_load_lds_dwordx4 v[150:151], off
	s_waitcnt lgkmcnt(8)
	s_barrier
	s_waitcnt lgkmcnt(0)
	s_setprio 1
	s_waitcnt lgkmcnt(0)
	v_mfma_f32_16x16x32_bf16 v[126:129], v[142:145], v[168:171], v[126:129]
	v_mfma_f32_16x16x32_bf16 v[122:125], v[160:163], v[168:171], v[122:125]
	v_mfma_f32_16x16x32_bf16 v[110:113], v[142:145], v[180:183], v[110:113]
	v_mfma_f32_16x16x32_bf16 v[106:109], v[160:163], v[180:183], v[106:109]
	v_mfma_f32_16x16x32_bf16 v[94:97], v[142:145], v[196:199], v[94:97]
	v_mfma_f32_16x16x32_bf16 v[90:93], v[160:163], v[196:199], v[90:93]
	v_mfma_f32_16x16x32_bf16 v[78:81], v[142:145], v[204:207], v[78:81]
	v_mfma_f32_16x16x32_bf16 v[74:77], v[160:163], v[204:207], v[74:77]
	v_mfma_f32_16x16x32_bf16 v[126:129], v[146:149], v[172:175], v[126:129]
	v_mfma_f32_16x16x32_bf16 v[122:125], v[164:167], v[172:175], v[122:125]
	v_mfma_f32_16x16x32_bf16 v[110:113], v[146:149], v[192:195], v[110:113]
	v_mfma_f32_16x16x32_bf16 v[106:109], v[164:167], v[192:195], v[106:109]
	v_mfma_f32_16x16x32_bf16 v[94:97], v[146:149], v[200:203], v[94:97]
	v_mfma_f32_16x16x32_bf16 v[90:93], v[164:167], v[200:203], v[90:93]
	v_mfma_f32_16x16x32_bf16 v[78:81], v[146:149], v[208:211], v[78:81]
	v_mfma_f32_16x16x32_bf16 v[74:77], v[164:167], v[208:211], v[74:77]
	s_setprio 0
	s_barrier
; #define PG8_STAGE(bufoff, gbase, voff) do { _Pragma("unroll") for (int _i = 0; _i < 2; ++_i) \
;         __builtin_amdgcn_global_load_lds((const unsigned*)((const char*)(gbase) + (voff)[_i]), (LAS unsigned*)(lds + (bufoff) + ldsw + _i * 8192), 16, 0, 0); } while (0)
; #define PG8_LDA(dst, b, h) do { _Pragma("unroll") for (int m = 0; m < 4; ++m) _Pragma("unroll") for (int k = 0; k < 2; ++k) dst[m][k] = *(const LAS bf16x8*)(lds + PG8_SA(b, h) + aoff + m * 2048 + k * 1024); } while (0)
; #define PG8_LDB(dst, b, h) do { _Pragma("unroll") for (int n = 0; n < 2; ++n) _Pragma("unroll") for (int k = 0; k < 2; ++k) dst[n][k] = *(const LAS bf16x8*)(lds + PG8_SB(b, h) + boff + n * 2048 + k * 1024); } while (0)
; #define PG8_MMA(ai, bj, At, Bt) do { __builtin_amdgcn_s_setprio(1); _Pragma("unroll") for (int m = 0; m < 4; ++m) _Pragma("unroll") for (int n = 0; n < 2; ++n) _Pragma("unroll") for (int k = 0; k < 2; ++k) \
;         acc[ai][bj][m][n] = __builtin_amdgcn_mfma_f32_16x16x32_bf16(Bt[n][k], At[m][k], acc[ai][bj][m][n], 0, 0, 0); __builtin_amdgcn_s_setprio(0); } while (0)
; #define PG8_WAIT_V(n) asm volatile("s_waitcnt vmcnt(" #n ")" ::: "memory")
; #define PG8_WAIT_L(n) asm volatile("s_waitcnt lgkmcnt(" #n ")" ::: "memory")
; #define PG8_BAR __builtin_amdgcn_s_barrier()
; #define PG8_SCHED __builtin_amdgcn_sched_barrier(0)
; template <class Epi, class Sched>
; __device__ __forceinline__ void gemm_phase(const int wv, LAS unsigned char* lds, const Gemm g, const Sched& S, const Epi& E) {
;     ...
;             PG8_WAIT_L(8); PG8_BAR; PG8_WAIT_L(0); PG8_MMA(0, 0, At, B0); PG8_BAR; PG8_SCHED;
;             PG8_LDB(B1, 0, 1); PG8_STAGE(PG8_SB(0, 0), b2, voffB);
;             PG8_BAR; PG8_WAIT_L(0); PG8_MMA(0, 1, At, B1); PG8_BAR;
;             PG8_LDA(At, 0, 1); PG8_STAGE(PG8_SA(0, 0), a2, voffA);
;             PG8_BAR; PG8_WAIT_L(0); PG8_MMA(1, 0, At, B0); PG8_BAR; PG8_SCHED;
;             PG8_STAGE(PG8_SB(0, 1), b2 + hstepB, voffB);
;             PG8_WAIT_V(6); PG8_BAR; PG8_MMA(1, 1, At, B1); PG8_BAR;
;             PG8_LDB(B0, 1, 0); PG8_SCHED; PG8_LDA(At, 1, 0); PG8_STAGE(PG8_SA(0, 1), a2 + hstepA, voffA);
	s_add_i32 s52, 0, 0x14000
	v_add_u32_e32 v150, s52, v152
	s_add_i32 s31, s31, s44
	ds_read_b128 v[212:215], v150
	ds_read_b128 v[216:219], v150 offset:1024
	ds_read_b128 v[220:223], v150 offset:2048
	ds_read_b128 v[224:227], v150 offset:3072
	v_lshl_add_u64 v[150:151], s[24:25], 0, v[132:133]
	s_mov_b32 m0, s31
	v_lshl_add_u64 v[176:177], s[24:25], 0, v[136:137]
	global_load_lds_dwordx4 v[150:151], off
	s_add_i32 m0, s31, 0x2000
	s_nop 0
	global_load_lds_dwordx4 v[176:177], off
	s_barrier
	s_waitcnt lgkmcnt(0)
	s_setprio 1
	s_waitcnt lgkmcnt(0)
	v_mfma_f32_16x16x32_bf16 v[118:121], v[212:215], v[168:171], v[118:121]
	v_mfma_f32_16x16x32_bf16 v[114:117], v[220:223], v[168:171], v[114:117]
	v_mfma_f32_16x16x32_bf16 v[102:105], v[212:215], v[180:183], v[102:105]
	v_mfma_f32_16x16x32_bf16 v[98:101], v[220:223], v[180:183], v[98:101]
	v_mfma_f32_16x16x32_bf16 v[86:89], v[212:215], v[196:199], v[86:89]
	v_mfma_f32_16x16x32_bf16 v[82:85], v[220:223], v[196:199], v[82:85]
	v_mfma_f32_16x16x32_bf16 v[70:73], v[212:215], v[204:207], v[70:73]
	v_mfma_f32_16x16x32_bf16 v[66:69], v[220:223], v[204:207], v[66:69]
	v_mfma_f32_16x16x32_bf16 v[118:121], v[216:219], v[172:175], v[118:121]
	v_mfma_f32_16x16x32_bf16 v[114:117], v[224:227], v[172:175], v[114:117]
	v_mfma_f32_16x16x32_bf16 v[102:105], v[216:219], v[192:195], v[102:105]
	v_mfma_f32_16x16x32_bf16 v[98:101], v[224:227], v[192:195], v[98:101]
	v_mfma_f32_16x16x32_bf16 v[86:89], v[216:219], v[200:203], v[86:89]
	v_mfma_f32_16x16x32_bf16 v[82:85], v[224:227], v[200:203], v[82:85]
	v_mfma_f32_16x16x32_bf16 v[70:73], v[216:219], v[208:211], v[70:73]
	v_mfma_f32_16x16x32_bf16 v[66:69], v[224:227], v[208:211], v[66:69]
	s_setprio 0
	s_mov_b32 m0, s45
	v_lshl_add_u64 v[228:229], s[26:27], 0, v[130:131]
	s_barrier
	ds_read_b128 v[168:171], v158 offset:16384
	ds_read_b128 v[172:175], v158 offset:17408
	ds_read_b128 v[180:183], v158 offset:18432
	ds_read_b128 v[192:195], v158 offset:19456
	ds_read_b128 v[196:199], v158 offset:20480
	ds_read_b128 v[200:203], v158 offset:21504
	ds_read_b128 v[204:207], v158 offset:22528
	ds_read_b128 v[208:211], v158 offset:23552
	global_load_lds_dwordx4 v[228:229], off
	v_lshl_add_u64 v[230:231], s[26:27], 0, v[134:135]
	s_mov_b32 m0, s46
	s_nop 0
	global_load_lds_dwordx4 v[230:231], off
	s_barrier
	s_waitcnt lgkmcnt(0)
	s_setprio 1
	s_waitcnt lgkmcnt(0)
	v_mfma_f32_16x16x32_bf16 v[62:65], v[142:145], v[168:171], v[62:65]
	v_mfma_f32_16x16x32_bf16 v[58:61], v[160:163], v[168:171], v[58:61]
	v_mfma_f32_16x16x32_bf16 v[46:49], v[142:145], v[180:183], v[46:49]
	v_mfma_f32_16x16x32_bf16 v[42:45], v[160:163], v[180:183], v[42:45]
	v_mfma_f32_16x16x32_bf16 v[30:33], v[142:145], v[196:199], v[30:33]
	v_mfma_f32_16x16x32_bf16 v[26:29], v[160:163], v[196:199], v[26:29]
	v_mfma_f32_16x16x32_bf16 v[14:17], v[142:145], v[204:207], v[14:17]
	v_mfma_f32_16x16x32_bf16 v[10:13], v[160:163], v[204:207], v[10:13]
	v_mfma_f32_16x16x32_bf16 v[62:65], v[146:149], v[172:175], v[62:65]
	v_mfma_f32_16x16x32_bf16 v[58:61], v[164:167], v[172:175], v[58:61]
	v_mfma_f32_16x16x32_bf16 v[46:49], v[146:149], v[192:195], v[46:49]
	v_mfma_f32_16x16x32_bf16 v[42:45], v[164:167], v[192:195], v[42:45]
	v_mfma_f32_16x16x32_bf16 v[30:33], v[146:149], v[200:203], v[30:33]
	v_mfma_f32_16x16x32_bf16 v[26:29], v[164:167], v[200:203], v[26:29]
	v_mfma_f32_16x16x32_bf16 v[14:17], v[146:149], v[208:211], v[14:17]
	v_mfma_f32_16x16x32_bf16 v[10:13], v[164:167], v[208:211], v[10:13]
	s_setprio 0
	s_waitcnt vmcnt(10)
	s_barrier
	s_add_u32 s34, s24, 0x40000
	s_addc_u32 s35, s25, 0
	s_add_i32 s31, s52, s44
	v_lshl_add_u64 v[142:143], s[34:35], 0, v[132:133]
	s_mov_b32 m0, s31
	s_nop 0
	global_load_lds_dwordx4 v[142:143], off
	v_lshl_add_u64 v[142:143], s[34:35], 0, v[136:137]
	s_add_i32 m0, s31, 0x2000
	s_nop 0
	global_load_lds_dwordx4 v[142:143], off
	s_waitcnt vmcnt(6)
	s_barrier
	s_setprio 1
	v_add_u32_e32 v159, 0x18000, v152
	v_mfma_f32_16x16x32_bf16 v[54:57], v[212:215], v[168:171], v[54:57]
	ds_read_b128 v[142:145], v159
	v_mfma_f32_16x16x32_bf16 v[50:53], v[220:223], v[168:171], v[50:53]
	ds_read_b128 v[146:149], v159 offset:1024
	v_mfma_f32_16x16x32_bf16 v[38:41], v[212:215], v[180:183], v[38:41]
	ds_read_b128 v[160:163], v159 offset:2048
	v_mfma_f32_16x16x32_bf16 v[34:37], v[220:223], v[180:183], v[34:37]
	ds_read_b128 v[164:167], v159 offset:3072
	v_mfma_f32_16x16x32_bf16 v[22:25], v[212:215], v[196:199], v[22:25]
	v_mfma_f32_16x16x32_bf16 v[18:21], v[220:223], v[196:199], v[18:21]
	v_mfma_f32_16x16x32_bf16 v[6:9], v[212:215], v[204:207], v[6:9]
	v_mfma_f32_16x16x32_bf16 v[2:5], v[220:223], v[204:207], v[2:5]
	v_mfma_f32_16x16x32_bf16 v[54:57], v[216:219], v[172:175], v[54:57]
	v_mfma_f32_16x16x32_bf16 v[50:53], v[224:227], v[172:175], v[50:53]
	v_mfma_f32_16x16x32_bf16 v[38:41], v[216:219], v[192:195], v[38:41]
	v_mfma_f32_16x16x32_bf16 v[34:37], v[224:227], v[192:195], v[34:37]
	v_mfma_f32_16x16x32_bf16 v[22:25], v[216:219], v[200:203], v[22:25]
	v_mfma_f32_16x16x32_bf16 v[18:21], v[224:227], v[200:203], v[18:21]
	v_mfma_f32_16x16x32_bf16 v[6:9], v[216:219], v[208:211], v[6:9]
	v_mfma_f32_16x16x32_bf16 v[2:5], v[224:227], v[208:211], v[2:5]
	s_setprio 0
	s_add_i32 s31, 0, 0x18000
	s_barrier
	s_add_u32 s26, s26, 0x40000
	s_addc_u32 s27, s27, 0
	s_mov_b32 m0, s47
	v_lshl_add_u64 v[212:213], s[26:27], 0, v[130:131]
	ds_read_b128 v[168:171], v158 offset:32768
	ds_read_b128 v[172:175], v158 offset:33792
	ds_read_b128 v[180:183], v158 offset:34816
	ds_read_b128 v[192:195], v158 offset:35840
	ds_read_b128 v[196:199], v158 offset:36864
	ds_read_b128 v[200:203], v158 offset:37888
	ds_read_b128 v[204:207], v158 offset:38912
	ds_read_b128 v[208:211], v158 offset:39936
	global_load_lds_dwordx4 v[212:213], off
	v_lshl_add_u64 v[212:213], s[26:27], 0, v[134:135]
	s_mov_b32 m0, s48
	s_nop 0
	global_load_lds_dwordx4 v[212:213], off
	s_waitcnt lgkmcnt(8)
	s_barrier
; #define PG8_STAGE(bufoff, gbase, voff) do { _Pragma("unroll") for (int _i = 0; _i < 2; ++_i) \
;         __builtin_amdgcn_global_load_lds((const unsigned*)((const char*)(gbase) + (voff)[_i]), (LAS unsigned*)(lds + (bufoff) + ldsw + _i * 8192), 16, 0, 0); } while (0)
; #define PG8_LDA(dst, b, h) do { _Pragma("unroll") for (int m = 0; m < 4; ++m) _Pragma("unroll") for (int k = 0; k < 2; ++k) dst[m][k] = *(const LAS bf16x8*)(lds + PG8_SA(b, h) + aoff + m * 2048 + k * 1024); } while (0)
; #define PG8_LDB(dst, b, h) do { _Pragma("unroll") for (int n = 0; n < 2; ++n) _Pragma("unroll") for (int k = 0; k < 2; ++k) dst[n][k] = *(const LAS bf16x8*)(lds + PG8_SB(b, h) + boff + n * 2048 + k * 1024); } while (0)
; #define PG8_MMA(ai, bj, At, Bt) do { __builtin_amdgcn_s_setprio(1); _Pragma("unroll") for (int m = 0; m < 4; ++m) _Pragma("unroll") for (int n = 0; n < 2; ++n) _Pragma("unroll") for (int k = 0; k < 2; ++k) \
;         acc[ai][bj][m][n] = __builtin_amdgcn_mfma_f32_16x16x32_bf16(Bt[n][k], At[m][k], acc[ai][bj][m][n], 0, 0, 0); __builtin_amdgcn_s_setprio(0); } while (0)
; #define PG8_WAIT_V(n) asm volatile("s_waitcnt vmcnt(" #n ")" ::: "memory")
; #define PG8_WAIT_L(n) asm volatile("s_waitcnt lgkmcnt(" #n ")" ::: "memory")
; #define PG8_BAR __builtin_amdgcn_s_barrier()
; #define PG8_SCHED __builtin_amdgcn_sched_barrier(0)
; template <class Epi, class Sched>
; __device__ __forceinline__ void gemm_phase(const int wv, LAS unsigned char* lds, const Gemm g, const Sched& S, const Epi& E) {
;     ...
;             PG8_WAIT_L(8); PG8_BAR; PG8_WAIT_L(0); PG8_MMA(0, 0, At, B0); PG8_BAR; PG8_SCHED;
;             PG8_LDB(B1, 1, 1); PG8_STAGE(PG8_SB(1, 0), b3, voffB);
;             PG8_BAR; PG8_WAIT_L(0); PG8_MMA(0, 1, At, B1); PG8_BAR;
;             PG8_LDA(At, 1, 1); PG8_STAGE(PG8_SA(1, 0), a3, voffA);
;             PG8_BAR; PG8_WAIT_L(0); PG8_MMA(1, 0, At, B0); PG8_BAR; PG8_SCHED;
;             PG8_STAGE(PG8_SB(1, 1), b3 + hstepB, voffB);
;             PG8_WAIT_V(6); PG8_BAR; PG8_MMA(1, 1, At, B1); PG8_BAR;
;         }
;         E(acc, cur, wr, wc, fr, fq); S.done(cur);
;         if (!has_next) break;
	s_waitcnt lgkmcnt(0)
	s_setprio 1
	s_waitcnt lgkmcnt(0)
	v_mfma_f32_16x16x32_bf16 v[126:129], v[142:145], v[168:171], v[126:129]
	v_mfma_f32_16x16x32_bf16 v[122:125], v[160:163], v[168:171], v[122:125]
	v_mfma_f32_16x16x32_bf16 v[110:113], v[142:145], v[180:183], v[110:113]
	v_mfma_f32_16x16x32_bf16 v[106:109], v[160:163], v[180:183], v[106:109]
	v_mfma_f32_16x16x32_bf16 v[94:97], v[142:145], v[196:199], v[94:97]
	v_mfma_f32_16x16x32_bf16 v[90:93], v[160:163], v[196:199], v[90:93]
	v_mfma_f32_16x16x32_bf16 v[78:81], v[142:145], v[204:207], v[78:81]
	v_mfma_f32_16x16x32_bf16 v[74:77], v[160:163], v[204:207], v[74:77]
	v_mfma_f32_16x16x32_bf16 v[126:129], v[146:149], v[172:175], v[126:129]
	v_mfma_f32_16x16x32_bf16 v[122:125], v[164:167], v[172:175], v[122:125]
	v_mfma_f32_16x16x32_bf16 v[110:113], v[146:149], v[192:195], v[110:113]
	v_mfma_f32_16x16x32_bf16 v[106:109], v[164:167], v[192:195], v[106:109]
	v_mfma_f32_16x16x32_bf16 v[94:97], v[146:149], v[200:203], v[94:97]
	v_mfma_f32_16x16x32_bf16 v[90:93], v[164:167], v[200:203], v[90:93]
	v_mfma_f32_16x16x32_bf16 v[78:81], v[146:149], v[208:211], v[78:81]
	v_mfma_f32_16x16x32_bf16 v[74:77], v[164:167], v[208:211], v[74:77]
	s_setprio 0
	s_barrier
	s_add_i32 s26, 0, 0x1c000
	s_add_i32 s27, s31, s44
	v_add_u32_e32 v159, s26, v152
	v_lshl_add_u64 v[150:151], v[150:151], 0, s[88:89]
	s_mov_b32 m0, s27
	ds_read_b128 v[212:215], v159
	ds_read_b128 v[216:219], v159 offset:1024
	ds_read_b128 v[220:223], v159 offset:2048
	ds_read_b128 v[224:227], v159 offset:3072
	global_load_lds_dwordx4 v[150:151], off
	v_lshl_add_u64 v[150:151], v[176:177], 0, s[88:89]
	s_add_i32 m0, s27, 0x2000
	s_nop 0
	global_load_lds_dwordx4 v[150:151], off
	s_barrier
	s_waitcnt lgkmcnt(0)
	s_setprio 1
	s_waitcnt lgkmcnt(0)
	v_mfma_f32_16x16x32_bf16 v[118:121], v[212:215], v[168:171], v[118:121]
	v_mfma_f32_16x16x32_bf16 v[114:117], v[220:223], v[168:171], v[114:117]
	v_mfma_f32_16x16x32_bf16 v[102:105], v[212:215], v[180:183], v[102:105]
	v_mfma_f32_16x16x32_bf16 v[98:101], v[220:223], v[180:183], v[98:101]
	v_mfma_f32_16x16x32_bf16 v[86:89], v[212:215], v[196:199], v[86:89]
	v_mfma_f32_16x16x32_bf16 v[82:85], v[220:223], v[196:199], v[82:85]
	v_mfma_f32_16x16x32_bf16 v[70:73], v[212:215], v[204:207], v[70:73]
	v_mfma_f32_16x16x32_bf16 v[66:69], v[220:223], v[204:207], v[66:69]
	v_mfma_f32_16x16x32_bf16 v[118:121], v[216:219], v[172:175], v[118:121]
	v_mfma_f32_16x16x32_bf16 v[114:117], v[224:227], v[172:175], v[114:117]
	v_mfma_f32_16x16x32_bf16 v[102:105], v[216:219], v[192:195], v[102:105]
	v_mfma_f32_16x16x32_bf16 v[98:101], v[224:227], v[192:195], v[98:101]
	v_mfma_f32_16x16x32_bf16 v[86:89], v[216:219], v[200:203], v[86:89]
	v_mfma_f32_16x16x32_bf16 v[82:85], v[224:227], v[200:203], v[82:85]
	v_mfma_f32_16x16x32_bf16 v[70:73], v[216:219], v[208:211], v[70:73]
	v_mfma_f32_16x16x32_bf16 v[66:69], v[224:227], v[208:211], v[66:69]
	s_setprio 0
	s_mov_b32 m0, s49
	v_lshl_add_u64 v[150:151], v[228:229], 0, s[88:89]
	s_barrier
	ds_read_b128 v[168:171], v158 offset:49152
	ds_read_b128 v[172:175], v158 offset:50176
	ds_read_b128 v[180:183], v158 offset:51200
	ds_read_b128 v[192:195], v158 offset:52224
	ds_read_b128 v[196:199], v158 offset:53248
	ds_read_b128 v[200:203], v158 offset:54272
	ds_read_b128 v[204:207], v158 offset:55296
	ds_read_b128 v[208:211], v158 offset:56320
	global_load_lds_dwordx4 v[150:151], off
	v_lshl_add_u64 v[150:151], v[230:231], 0, s[88:89]
	s_mov_b32 m0, s50
	s_nop 0
	global_load_lds_dwordx4 v[150:151], off
	s_barrier
	s_waitcnt lgkmcnt(0)
	s_setprio 1
	s_waitcnt lgkmcnt(0)
	v_mfma_f32_16x16x32_bf16 v[62:65], v[142:145], v[168:171], v[62:65]
	v_mfma_f32_16x16x32_bf16 v[58:61], v[160:163], v[168:171], v[58:61]
	v_mfma_f32_16x16x32_bf16 v[46:49], v[142:145], v[180:183], v[46:49]
	v_mfma_f32_16x16x32_bf16 v[42:45], v[160:163], v[180:183], v[42:45]
	v_mfma_f32_16x16x32_bf16 v[30:33], v[142:145], v[196:199], v[30:33]
	v_mfma_f32_16x16x32_bf16 v[26:29], v[160:163], v[196:199], v[26:29]
	v_mfma_f32_16x16x32_bf16 v[14:17], v[142:145], v[204:207], v[14:17]
	v_mfma_f32_16x16x32_bf16 v[10:13], v[160:163], v[204:207], v[10:13]
	v_mfma_f32_16x16x32_bf16 v[62:65], v[146:149], v[172:175], v[62:65]
	v_mfma_f32_16x16x32_bf16 v[58:61], v[164:167], v[172:175], v[58:61]
	v_mfma_f32_16x16x32_bf16 v[46:49], v[146:149], v[192:195], v[46:49]
	v_mfma_f32_16x16x32_bf16 v[42:45], v[164:167], v[192:195], v[42:45]
	v_mfma_f32_16x16x32_bf16 v[30:33], v[146:149], v[200:203], v[30:33]
	v_mfma_f32_16x16x32_bf16 v[26:29], v[164:167], v[200:203], v[26:29]
	v_mfma_f32_16x16x32_bf16 v[14:17], v[146:149], v[208:211], v[14:17]
	v_mfma_f32_16x16x32_bf16 v[10:13], v[164:167], v[208:211], v[10:13]
	s_setprio 0
	s_waitcnt vmcnt(10)
	s_barrier
	s_add_u32 s24, s24, 0x40080
	s_addc_u32 s25, s25, 0
	s_add_i32 s26, s26, s44
	v_lshl_add_u64 v[142:143], s[24:25], 0, v[132:133]
	s_mov_b32 m0, s26
	s_nop 0
	global_load_lds_dwordx4 v[142:143], off
	v_lshl_add_u64 v[142:143], s[24:25], 0, v[136:137]
	s_add_i32 m0, s26, 0x2000
	s_nop 0
	global_load_lds_dwordx4 v[142:143], off
	s_waitcnt vmcnt(6)
	s_barrier
	s_setprio 1
	v_add_u32_e32 v150, 0x10000, v152
	v_mfma_f32_16x16x32_bf16 v[54:57], v[212:215], v[168:171], v[54:57]
	ds_read_b128 v[142:145], v150
	v_mfma_f32_16x16x32_bf16 v[50:53], v[220:223], v[168:171], v[50:53]
	ds_read_b128 v[146:149], v150 offset:1024
	v_mfma_f32_16x16x32_bf16 v[38:41], v[212:215], v[180:183], v[38:41]
	ds_read_b128 v[160:163], v150 offset:2048
	v_mfma_f32_16x16x32_bf16 v[34:37], v[220:223], v[180:183], v[34:37]
	ds_read_b128 v[164:167], v150 offset:3072
	v_mfma_f32_16x16x32_bf16 v[22:25], v[212:215], v[196:199], v[22:25]
	v_mfma_f32_16x16x32_bf16 v[18:21], v[220:223], v[196:199], v[18:21]
	v_mfma_f32_16x16x32_bf16 v[6:9], v[212:215], v[204:207], v[6:9]
	v_mfma_f32_16x16x32_bf16 v[2:5], v[220:223], v[204:207], v[2:5]
	v_mfma_f32_16x16x32_bf16 v[54:57], v[216:219], v[172:175], v[54:57]
	v_mfma_f32_16x16x32_bf16 v[50:53], v[224:227], v[172:175], v[50:53]
	v_mfma_f32_16x16x32_bf16 v[38:41], v[216:219], v[192:195], v[38:41]
	v_mfma_f32_16x16x32_bf16 v[34:37], v[224:227], v[192:195], v[34:37]
	v_mfma_f32_16x16x32_bf16 v[22:25], v[216:219], v[200:203], v[22:25]
	v_mfma_f32_16x16x32_bf16 v[18:21], v[224:227], v[200:203], v[18:21]
	v_mfma_f32_16x16x32_bf16 v[6:9], v[216:219], v[208:211], v[6:9]
	v_mfma_f32_16x16x32_bf16 v[2:5], v[224:227], v[208:211], v[2:5]
	s_setprio 0
	s_add_i32 s30, s30, 2
	s_add_u32 s22, s22, 0x100
	s_addc_u32 s23, s23, 0
	s_add_u32 s28, s28, 0x100
	s_addc_u32 s29, s29, 0
	s_cmp_gt_u32 s30, 13
	s_barrier
	s_cbranch_scc0 .LBB0_147
	s_waitcnt lgkmcnt(0)
	s_cmp_gt_i32 s0, 33
	s_mov_b64 s[22:23], -1
	s_cbranch_scc0 .LBB0_153
	s_lshl_b32 s1, s0, 8
	s_cmp_gt_u32 s0, 41
	s_mov_b64 s[28:29], -1
	s_mov_b64 s[24:25], -1
	s_cbranch_scc0 .LBB0_151
	s_add_i32 s3, s1, 0xffffd600
	s_mov_b64 s[24:25], 0
